# speedup vs baseline: 1.0047x; 1.0047x over previous
; DEVINL int opaque_tid(int wv) { int t = (wv << 6) | (int)__builtin_amdgcn_mbcnt_hi(~0u, __builtin_amdgcn_mbcnt_lo(~0u, 0u)); asm volatile("" : "+v"(t)); return t; }
; DEVINL int item_request(int* ctr, int wv) { int pend = 0; if (opaque_tid(wv) == 0) pend = atomicAdd(ctr, 1); return pend; }
; DEVINL void phase_topk(const Params& p, int layer, char* smem, int wv, int rep) {
;     ...
;   int gi = next_item(ctr, smem, wv);
;   {
;     const int tid = opaque_tid(wv), lane = tid & 63, fr = lane & 15, fq = lane >> 4;
;     if (gi < T_TOK / 8) LOADQ(gi);
;   }
;   while (gi < T_TOK / 8) {
;     const int pend = item_request(ctr, wv);
.LBB0_462:
.LBB0_463:
	s_add_u32 s48, s94, 0x19103700
	s_addc_u32 s49, s95, 0
	s_add_u32 s80, s94, 0x1d303700
	s_addc_u32 s81, s95, 0
	s_andn2_b64 vcc, exec, s[0:1]
	s_cbranch_vccnz .LBB0_546
	s_add_u32 s18, s94, 0x19124f40
	s_addc_u32 s19, s95, 0
	s_mov_b32 s21, 0
	v_mov_b32_e32 v161, 0
	s_add_i32 s33, 0, 0x20000
	v_cmp_eq_u32_e32 vcc, 0, v176
	s_and_saveexec_b64 s[98:99], vcc
	s_cbranch_execz .Lreq_q0a
	v_mov_b32_e32 v252, 0
	v_mov_b32_e32 v253, 1
	global_atomic_add v253, v252, v253, s[16:17] sc0
.Lreq_q0a:
	s_or_b64 exec, exec, s[98:99]
	s_branch .LBB0_466

; DEVINL int opaque_tid(int wv) { int t = (wv << 6) | (int)__builtin_amdgcn_mbcnt_hi(~0u, __builtin_amdgcn_mbcnt_lo(~0u, 0u)); asm volatile("" : "+v"(t)); return t; }
; DEVINL int item_request(int* ctr, int wv) { int pend = 0; if (opaque_tid(wv) == 0) pend = atomicAdd(ctr, 1); return pend; }
; #define LOADG(S, GRP) do { const u16* _k = kb + (size_t)(GRP) * 4096; \
;       _Pragma("unroll") for (int _i = 0; _i < 4; ++_i) { kf[S][2 * _i] = *(const bf16x8*)(_k + _i * 1024); kf[S][2 * _i + 1] = *(const bf16x8*)(_k + _i * 1024 + 32); } } while (0)
; DEVINL void phase_topk(const Params& p, int layer, char* smem, int wv, int rep) {
;     ...
;     const int pend = item_request(ctr, wv);
;     __syncthreads();
;     const int tid = opaque_tid(wv), lane = tid & 63, wid = __builtin_amdgcn_readfirstlane(tid >> 6), fr = lane & 15, fq = lane >> 4;
;     const int b = gi & 3, t0 = (511 - (gi >> 2)) * 8;
;     const int ng = (t0 >> 6) + 1;
;     const u16* kb = kin + (size_t)b * SEQ * 64 + (size_t)fr * 64 + fq * 8;
;     bf16x8 kf[2][8];
;     ...
;     {
;       int g = wid;
;       if (g < ng) LOADG(0, g);
;       for (; g < ng; g += 16) {
;         if (g + 8 < ng) LOADG(1, g + 8);
.LBB0_469:
.LBB0_470:
	v_mov_b32_e32 v166, v176
	s_barrier
	s_nop 0
	v_readfirstlane_b32 s0, v166
	s_ashr_i32 s2, s0, 6
	s_lshl_b32 s0, s39, 1
	s_and_b32 s0, s0, -8
	s_sub_i32 s6, 0xff8, s0
	s_lshl_b32 s0, s39, 12
	s_and_b32 s38, s0, 0x3000
	v_bfe_u32 v163, v166, 4, 2
	s_lshr_b32 s4, s6, 6
	s_lshl_b32 s5, s38, 7
	v_lshlrev_b32_e32 v160, 6, v166
	v_and_b32_e32 v160, 0x3c0, v160
	v_lshlrev_b32_e32 v162, 3, v163
	s_cmp_le_i32 s2, s4
	s_cselect_b64 s[0:1], -1, 0
	s_cmp_gt_i32 s2, s4
	v_lshlrev_b32_e32 v160, 1, v160
	v_lshlrev_b32_e32 v164, 1, v162
	s_cbranch_scc1 .LBB0_472
	s_add_u32 s8, s48, s5
	s_addc_u32 s9, s49, 0
	s_waitcnt vmcnt(8)
	v_lshl_add_u64 v[124:125], s[8:9], 0, v[160:161]
	v_mov_b32_e32 v165, v161
	s_ashr_i32 s3, s2, 31
	v_lshl_add_u64 v[124:125], v[124:125], 0, v[164:165]
	s_lshl_b64 s[8:9], s[2:3], 13
	s_waitcnt vmcnt(4)
	v_lshl_add_u64 v[144:145], v[124:125], 0, s[8:9]
	s_waitcnt vmcnt(1)
	v_add_co_u32_e32 v156, vcc, 0x1000, v144
	global_load_dwordx4 v[124:127], v[144:145], off
	global_load_dwordx4 v[128:131], v[144:145], off offset:64
	global_load_dwordx4 v[132:135], v[144:145], off offset:2048
	global_load_dwordx4 v[136:139], v[144:145], off offset:2112
	v_addc_co_u32_e32 v157, vcc, 0, v145, vcc
	global_load_dwordx4 v[144:147], v[156:157], off
	global_load_dwordx4 v[148:151], v[156:157], off offset:64
	global_load_dwordx4 v[152:155], v[156:157], off offset:2048
	s_nop 0
	global_load_dwordx4 v[156:159], v[156:157], off offset:2112

; DEVINL int opaque_tid(int wv) { int t = (wv << 6) | (int)__builtin_amdgcn_mbcnt_hi(~0u, __builtin_amdgcn_mbcnt_lo(~0u, 0u)); asm volatile("" : "+v"(t)); return t; }
; DEVINL int item_request(int* ctr, int wv) { int pend = 0; if (opaque_tid(wv) == 0) pend = atomicAdd(ctr, 1); return pend; }
; #define LOADG(S, GRP) do { const u16* _k = kb + (size_t)(GRP) * 4096; \
;       _Pragma("unroll") for (int _i = 0; _i < 4; ++_i) { kf[S][2 * _i] = *(const bf16x8*)(_k + _i * 1024); kf[S][2 * _i + 1] = *(const bf16x8*)(_k + _i * 1024 + 32); } } while (0)
; DEVINL int item_collect(int pend, char* smem, int wv) {
;   int* slot = (int*)(smem + SMEM_MAIN);
;   __syncthreads();
;   if (opaque_tid(wv) == 0) *slot = pend;
;   __syncthreads();
;   return *slot;
; }
; DEVINL void phase_topk(const Params& p, int layer, char* smem, int wv, int rep) {
;     ...
;   int gi = next_item(ctr, smem, wv);
;   {
;     const int tid = opaque_tid(wv), lane = tid & 63, fr = lane & 15, fq = lane >> 4;
;     if (gi < T_TOK / 8) LOADQ(gi);
;   }
;   while (gi < T_TOK / 8) {
;     const int pend = item_request(ctr, wv);
;     __syncthreads();
;     const int tid = opaque_tid(wv), lane = tid & 63, wid = __builtin_amdgcn_readfirstlane(tid >> 6), fr = lane & 15, fq = lane >> 4;
;     const int b = gi & 3, t0 = (511 - (gi >> 2)) * 8;
;     const int ng = (t0 >> 6) + 1;
;     const u16* kb = kin + (size_t)b * SEQ * 64 + (size_t)fr * 64 + fq * 8;
;     bf16x8 kf[2][8];
;     ...
;     {
;       int g = wid;
;       if (g < ng) LOADG(0, g);
;       for (; g < ng; g += 16) {
;         if (g + 8 < ng) LOADG(1, g + 8);
;         COMPUTEG(0, g);
;         if (g + 8 < ng) {
;           if (g + 16 < ng) LOADG(0, g + 16);
;           COMPUTEG(1, g + 8);
;         }
;       }
;     }
;     ...
;     const int gi_next = item_collect(pend, smem, wv);
;     if (gi_next < T_TOK / 8) LOADQ(gi_next);
.LBB0_481:
	v_mov_b32_e32 v165, v176
	s_waitcnt lgkmcnt(0)
	s_barrier
	s_nop 0
	v_cmp_eq_u32_e32 vcc, 0, v165
	s_and_saveexec_b64 s[0:1], vcc
	v_mov_b32_e32 v165, s33
	s_waitcnt vmcnt(0)
	ds_write_b32 v165, v253
	s_or_b64 exec, exec, s[0:1]
	v_mov_b32_e32 v165, s33
	s_waitcnt lgkmcnt(0)
	s_barrier
	ds_read_b32 v165, v165
	s_movk_i32 s0, 0x7ff
	s_waitcnt lgkmcnt(0)
	v_cmp_lt_i32_e64 s[0:1], s0, v165
	v_readfirstlane_b32 s39, v165
	s_and_b64 vcc, exec, s[0:1]
	s_cbranch_vccnz .LBB0_485
	s_lshl_b32 s3, s39, 1
	s_lshl_b32 s4, s39, 12
	s_and_b32 s3, s3, -8
	s_and_b32 s4, s4, 0x3000
	s_sub_i32 s3, s4, s3
	s_add_i32 s20, s3, 0xff8
	s_mul_i32 s4, s20, 0x2800
	s_mul_hi_u32 s3, s20, 0x2800
	s_add_u32 s4, s70, s4
	s_waitcnt vmcnt(23)
	v_lshlrev_b32_e32 v0, 4, v163
	v_mov_b32_e32 v1, v161
	s_addc_u32 s5, s71, s3
	s_waitcnt vmcnt(0)
	v_lshl_add_u64 v[140:141], s[46:47], 0, v[0:1]
	v_mov_b32_e32 v165, v161
	v_lshl_add_u64 v[0:1], s[4:5], 0, v[160:161]
	v_lshl_add_u64 v[100:101], v[0:1], 0, v[164:165]
	s_movk_i32 s3, 0x2000
	s_mov_b64 s[4:5], 0x2000
	v_add_co_u32_e32 v0, vcc, s3, v100
	v_lshl_add_u64 v[4:5], v[100:101], 0, s[4:5]
	s_nop 0
	v_addc_co_u32_e32 v1, vcc, 0, v101, vcc
	s_lshl_b64 s[4:5], s[20:21], 6
	s_mov_b64 s[8:9], 0x4800
	s_movk_i32 s3, 0x4000
	v_lshl_add_u64 v[10:11], v[100:101], 0, s[8:9]
	v_add_co_u32_e32 v16, vcc, s3, v100
	s_or_b32 s8, s4, 64
	s_mov_b32 s9, s5
	v_addc_co_u32_e32 v17, vcc, 0, v101, vcc
	v_lshl_add_u64 v[20:21], v[140:141], 0, s[8:9]
	s_mov_b64 s[8:9], 0x7000
	s_movk_i32 s3, 0x7000
	v_lshl_add_u64 v[28:29], v[100:101], 0, s[8:9]
	v_add_co_u32_e32 v24, vcc, s3, v100
	s_or_b32 s8, s4, 0x80
	s_mov_b32 s9, s5
	v_addc_co_u32_e32 v25, vcc, 0, v101, vcc
	v_lshl_add_u64 v[32:33], v[140:141], 0, s[8:9]
	s_mov_b64 s[8:9], 0x9800
	s_mov_b32 s3, 0x9000
	v_lshl_add_u64 v[34:35], v[100:101], 0, s[8:9]
	v_add_co_u32_e32 v40, vcc, s3, v100
	s_or_b32 s8, s4, 0xc0
	s_mov_b32 s9, s5
	v_addc_co_u32_e32 v41, vcc, 0, v101, vcc
	v_lshl_add_u64 v[44:45], v[140:141], 0, s[8:9]
	s_mov_b64 s[8:9], 0xc000
	s_mov_b32 s3, 0xc000
	v_lshl_add_u64 v[48:49], v[100:101], 0, s[8:9]
	v_add_co_u32_e32 v52, vcc, s3, v100
	s_or_b32 s8, s4, 0x100
	s_mov_b32 s9, s5
	v_addc_co_u32_e32 v53, vcc, 0, v101, vcc
	v_lshl_add_u64 v[56:57], v[140:141], 0, s[8:9]
	s_mov_b64 s[8:9], 0xe800
	s_mov_b32 s3, 0xe000
	v_lshl_add_u64 v[64:65], v[100:101], 0, s[8:9]
	v_add_co_u32_e32 v60, vcc, s3, v100
	s_or_b32 s8, s4, 0x140
	s_mov_b32 s9, s5
	v_addc_co_u32_e32 v61, vcc, 0, v101, vcc
	v_lshl_add_u64 v[68:69], v[140:141], 0, s[8:9]
	s_mov_b64 s[8:9], 0x11000
	s_mov_b32 s3, 0x11000
	v_lshl_add_u64 v[76:77], v[100:101], 0, s[8:9]
	v_add_co_u32_e32 v72, vcc, s3, v100
	s_or_b32 s8, s4, 0x180
	s_mov_b32 s9, s5
	v_addc_co_u32_e32 v73, vcc, 0, v101, vcc
	v_lshl_add_u64 v[80:81], v[140:141], 0, s[8:9]
	s_mov_b64 s[8:9], 0x13800
	v_lshl_add_u64 v[8:9], v[140:141], 0, s[4:5]
	v_lshl_add_u64 v[104:105], v[100:101], 0, s[8:9]
	v_add_co_u32_e32 v100, vcc, 0x13000, v100
	s_or_b32 s4, s4, 0x1c0
	s_nop 0
	v_addc_co_u32_e32 v101, vcc, 0, v101, vcc
	v_lshl_add_u64 v[140:141], v[140:141], 0, s[4:5]
	global_load_dwordx4 v[0:3], v[0:1], off
	s_nop 0
	global_load_dwordx4 v[4:7], v[4:5], off offset:64
	s_nop 0
	global_load_dwordx4 v[12:15], v[8:9], off
	s_nop 0
	global_load_dwordx4 v[8:11], v[10:11], off offset:64
	s_nop 0
	global_load_dwordx4 v[16:19], v[16:17], off offset:2048
	s_nop 0
	global_load_dwordx4 v[20:23], v[20:21], off
	s_nop 0
	global_load_dwordx4 v[24:27], v[24:25], off
	s_nop 0
	global_load_dwordx4 v[28:31], v[28:29], off offset:64
	s_nop 0
	global_load_dwordx4 v[36:39], v[32:33], off
	s_nop 0
	global_load_dwordx4 v[32:35], v[34:35], off offset:64
	s_nop 0
	global_load_dwordx4 v[40:43], v[40:41], off offset:2048
	s_nop 0
	global_load_dwordx4 v[44:47], v[44:45], off
	s_nop 0
	global_load_dwordx4 v[48:51], v[48:49], off offset:64
	s_nop 0
	global_load_dwordx4 v[52:55], v[52:53], off
	s_nop 0
	global_load_dwordx4 v[56:59], v[56:57], off
	s_nop 0
	global_load_dwordx4 v[60:63], v[60:61], off offset:2048
	s_nop 0
	global_load_dwordx4 v[64:67], v[64:65], off offset:64
	s_nop 0
	global_load_dwordx4 v[68:71], v[68:69], off
	s_nop 0
	global_load_dwordx4 v[72:75], v[72:73], off
	s_nop 0
	global_load_dwordx4 v[76:79], v[76:77], off offset:64
	s_nop 0
	global_load_dwordx4 v[80:83], v[80:81], off
	s_nop 0
	global_load_dwordx4 v[100:103], v[100:101], off offset:2048
	s_nop 0
	global_load_dwordx4 v[104:107], v[104:105], off offset:64
	s_nop 0
	global_load_dwordx4 v[140:143], v[140:141], off
	v_cmp_eq_u32_e32 vcc, 0, v176
	s_and_saveexec_b64 s[98:99], vcc
	s_cbranch_execz .Lreq_q0b
	v_mov_b32_e32 v252, 0
	v_mov_b32_e32 v253, 1
	global_atomic_add v253, v252, v253, s[16:17] sc0
.Lreq_q0b:
	s_or_b64 exec, exec, s[98:99]

; DEVINL int opaque_tid(int wv) { int t = (wv << 6) | (int)__builtin_amdgcn_mbcnt_hi(~0u, __builtin_amdgcn_mbcnt_lo(~0u, 0u)); asm volatile("" : "+v"(t)); return t; }
; DEVINL int item_request(int* ctr, int wv) { int pend = 0; if (opaque_tid(wv) == 0) pend = atomicAdd(ctr, 1); return pend; }
; DEVINL void phase_topk(const Params& p, int layer, char* smem, int wv, int rep) {
;     ...
;   int gi = next_item(ctr, smem, wv);
;   {
;     const int tid = opaque_tid(wv), lane = tid & 63, fr = lane & 15, fq = lane >> 4;
;     if (gi < T_TOK / 8) LOADQ(gi);
;   }
;   while (gi < T_TOK / 8) {
;     const int pend = item_request(ctr, wv);
.LBB0_1486:
	s_add_u32 s20, s94, 0x19124f40
	s_addc_u32 s21, s95, 0
	s_mov_b32 s23, 0
	v_mov_b32_e32 v161, 0
	s_add_i32 s40, 0, 0x20000
	v_cmp_eq_u32_e32 vcc, 0, v176
	s_and_saveexec_b64 s[98:99], vcc
	s_cbranch_execz .Lreq_q1a
	v_mov_b32_e32 v252, 0
	v_mov_b32_e32 v253, 1
	global_atomic_add v253, v252, v253, s[18:19] sc0

; DEVINL int opaque_tid(int wv) { int t = (wv << 6) | (int)__builtin_amdgcn_mbcnt_hi(~0u, __builtin_amdgcn_mbcnt_lo(~0u, 0u)); asm volatile("" : "+v"(t)); return t; }
; DEVINL int item_request(int* ctr, int wv) { int pend = 0; if (opaque_tid(wv) == 0) pend = atomicAdd(ctr, 1); return pend; }
; #define LOADG(S, GRP) do { const u16* _k = kb + (size_t)(GRP) * 4096; \
;       _Pragma("unroll") for (int _i = 0; _i < 4; ++_i) { kf[S][2 * _i] = *(const bf16x8*)(_k + _i * 1024); kf[S][2 * _i + 1] = *(const bf16x8*)(_k + _i * 1024 + 32); } } while (0)
; DEVINL void phase_topk(const Params& p, int layer, char* smem, int wv, int rep) {
;     ...
;     const int pend = item_request(ctr, wv);
;     __syncthreads();
;     const int tid = opaque_tid(wv), lane = tid & 63, wid = __builtin_amdgcn_readfirstlane(tid >> 6), fr = lane & 15, fq = lane >> 4;
;     const int b = gi & 3, t0 = (511 - (gi >> 2)) * 8;
;     const int ng = (t0 >> 6) + 1;
;     const u16* kb = kin + (size_t)b * SEQ * 64 + (size_t)fr * 64 + fq * 8;
;     bf16x8 kf[2][8];
;     ...
;     {
;       int g = wid;
;       if (g < ng) LOADG(0, g);
;       for (; g < ng; g += 16) {
;         if (g + 8 < ng) LOADG(1, g + 8);
.LBB0_1491:
.LBB0_1492:
	v_mov_b32_e32 v166, v176
	s_barrier
	s_nop 0
	v_readfirstlane_b32 s0, v166
	s_ashr_i32 s4, s0, 6
	s_lshl_b32 s0, s33, 1
	s_and_b32 s0, s0, -8
	s_sub_i32 s8, 0xff8, s0
	s_lshl_b32 s0, s33, 12
	s_and_b32 s41, s0, 0x3000
	v_bfe_u32 v163, v166, 4, 2
	s_lshr_b32 s6, s8, 6
	s_lshl_b32 s0, s41, 7
	v_lshlrev_b32_e32 v160, 6, v166
	v_and_b32_e32 v160, 0x3c0, v160
	v_lshlrev_b32_e32 v162, 3, v163
	s_cmp_le_i32 s4, s6
	s_cselect_b64 s[2:3], -1, 0
	s_cmp_gt_i32 s4, s6
	v_lshlrev_b32_e32 v160, 1, v160
	v_lshlrev_b32_e32 v164, 1, v162
	s_cbranch_scc1 .LBB0_1494
	s_add_u32 s10, s72, s0
	s_addc_u32 s11, s73, 0
	s_waitcnt vmcnt(8)
	v_lshl_add_u64 v[124:125], s[10:11], 0, v[160:161]
	v_mov_b32_e32 v165, v161
	s_ashr_i32 s5, s4, 31
	v_lshl_add_u64 v[124:125], v[124:125], 0, v[164:165]
	s_lshl_b64 s[10:11], s[4:5], 13
	s_waitcnt vmcnt(0)
	v_lshl_add_u64 v[140:141], v[124:125], 0, s[10:11]
	v_add_co_u32_e32 v156, vcc, 0x1000, v140
	global_load_dwordx4 v[124:127], v[140:141], off
	global_load_dwordx4 v[128:131], v[140:141], off offset:64
	global_load_dwordx4 v[132:135], v[140:141], off offset:2048
	global_load_dwordx4 v[136:139], v[140:141], off offset:2112
	v_addc_co_u32_e32 v157, vcc, 0, v141, vcc
	global_load_dwordx4 v[140:143], v[156:157], off
	global_load_dwordx4 v[144:147], v[156:157], off offset:64
	global_load_dwordx4 v[152:155], v[156:157], off offset:2048
	s_nop 0
	global_load_dwordx4 v[156:159], v[156:157], off offset:2112

; DEVINL int opaque_tid(int wv) { int t = (wv << 6) | (int)__builtin_amdgcn_mbcnt_hi(~0u, __builtin_amdgcn_mbcnt_lo(~0u, 0u)); asm volatile("" : "+v"(t)); return t; }
; DEVINL int item_request(int* ctr, int wv) { int pend = 0; if (opaque_tid(wv) == 0) pend = atomicAdd(ctr, 1); return pend; }
; #define LOADG(S, GRP) do { const u16* _k = kb + (size_t)(GRP) * 4096; \
;       _Pragma("unroll") for (int _i = 0; _i < 4; ++_i) { kf[S][2 * _i] = *(const bf16x8*)(_k + _i * 1024); kf[S][2 * _i + 1] = *(const bf16x8*)(_k + _i * 1024 + 32); } } while (0)
; DEVINL int item_collect(int pend, char* smem, int wv) {
;   int* slot = (int*)(smem + SMEM_MAIN);
;   __syncthreads();
;   if (opaque_tid(wv) == 0) *slot = pend;
;   __syncthreads();
;   return *slot;
; }
; DEVINL void phase_topk(const Params& p, int layer, char* smem, int wv, int rep) {
;     ...
;   int gi = next_item(ctr, smem, wv);
;   {
;     const int tid = opaque_tid(wv), lane = tid & 63, fr = lane & 15, fq = lane >> 4;
;     if (gi < T_TOK / 8) LOADQ(gi);
;   }
;   while (gi < T_TOK / 8) {
;     const int pend = item_request(ctr, wv);
;     __syncthreads();
;     const int tid = opaque_tid(wv), lane = tid & 63, wid = __builtin_amdgcn_readfirstlane(tid >> 6), fr = lane & 15, fq = lane >> 4;
;     const int b = gi & 3, t0 = (511 - (gi >> 2)) * 8;
;     const int ng = (t0 >> 6) + 1;
;     const u16* kb = kin + (size_t)b * SEQ * 64 + (size_t)fr * 64 + fq * 8;
;     bf16x8 kf[2][8];
;     ...
;     {
;       int g = wid;
;       if (g < ng) LOADG(0, g);
;       for (; g < ng; g += 16) {
;         if (g + 8 < ng) LOADG(1, g + 8);
;         COMPUTEG(0, g);
;         if (g + 8 < ng) {
;           if (g + 16 < ng) LOADG(0, g + 16);
;           COMPUTEG(1, g + 8);
;         }
;       }
;     }
;     ...
;     const int gi_next = item_collect(pend, smem, wv);
;     if (gi_next < T_TOK / 8) LOADQ(gi_next);
.LBB0_1503:
	v_mov_b32_e32 v165, v176
	s_waitcnt lgkmcnt(0)
	s_barrier
	s_nop 0
	v_cmp_eq_u32_e32 vcc, 0, v165
	s_and_saveexec_b64 s[2:3], vcc
	v_mov_b32_e32 v165, s40
	s_waitcnt vmcnt(0)
	ds_write_b32 v165, v253
	s_or_b64 exec, exec, s[2:3]
	v_mov_b32_e32 v165, s40
	s_waitcnt lgkmcnt(0)
	s_barrier
	ds_read_b32 v165, v165
	s_movk_i32 s0, 0x7ff
	s_waitcnt lgkmcnt(0)
	v_cmp_lt_i32_e64 s[2:3], s0, v165
	v_readfirstlane_b32 s33, v165
	s_and_b64 vcc, exec, s[2:3]
	s_cbranch_vccnz .LBB0_1507
	s_lshl_b32 s0, s33, 1
	s_lshl_b32 s1, s33, 12
	s_and_b32 s0, s0, -8
	s_and_b32 s1, s1, 0x3000
	s_sub_i32 s0, s1, s0
	s_add_i32 s22, s0, 0xff8
	s_mul_i32 s0, s22, 0x2800
	s_mul_hi_u32 s1, s22, 0x2800
	s_add_u32 s0, s62, s0
	v_lshlrev_b32_e32 v0, 4, v163
	v_mov_b32_e32 v1, v161
	s_addc_u32 s1, s63, s1
	s_waitcnt vmcnt(0)
	v_lshl_add_u64 v[148:149], s[64:65], 0, v[0:1]
	v_mov_b32_e32 v165, v161
	v_lshl_add_u64 v[0:1], s[0:1], 0, v[160:161]
	v_lshl_add_u64 v[116:117], v[0:1], 0, v[164:165]
	s_mov_b64 s[0:1], 0x2000
	v_lshl_add_u64 v[4:5], v[116:117], 0, s[0:1]
	s_movk_i32 s0, 0x2000
	v_add_co_u32_e32 v0, vcc, s0, v116
	s_mov_b64 s[0:1], 0x4800
	s_nop 0
	v_addc_co_u32_e32 v1, vcc, 0, v117, vcc
	s_lshl_b64 s[6:7], s[22:23], 6
	v_lshl_add_u64 v[10:11], v[116:117], 0, s[0:1]
	s_movk_i32 s0, 0x4000
	v_add_co_u32_e32 v16, vcc, s0, v116
	s_or_b32 s0, s6, 64
	s_mov_b32 s1, s7
	v_lshl_add_u64 v[20:21], v[148:149], 0, s[0:1]
	s_mov_b64 s[0:1], 0x7000
	v_addc_co_u32_e32 v17, vcc, 0, v117, vcc
	v_lshl_add_u64 v[28:29], v[116:117], 0, s[0:1]
	s_movk_i32 s0, 0x7000
	v_add_co_u32_e32 v24, vcc, s0, v116
	s_or_b32 s0, s6, 0x80
	s_mov_b32 s1, s7
	v_lshl_add_u64 v[32:33], v[148:149], 0, s[0:1]
	s_mov_b64 s[0:1], 0x9800
	v_addc_co_u32_e32 v25, vcc, 0, v117, vcc
	v_lshl_add_u64 v[34:35], v[116:117], 0, s[0:1]
	s_mov_b32 s0, 0x9000
	v_add_co_u32_e32 v40, vcc, s0, v116
	s_or_b32 s0, s6, 0xc0
	s_mov_b32 s1, s7
	v_lshl_add_u64 v[44:45], v[148:149], 0, s[0:1]
	s_mov_b64 s[0:1], 0xc000
	v_addc_co_u32_e32 v41, vcc, 0, v117, vcc
	v_lshl_add_u64 v[48:49], v[116:117], 0, s[0:1]
	s_mov_b32 s0, 0xc000
	v_add_co_u32_e32 v52, vcc, s0, v116
	s_or_b32 s0, s6, 0x100
	s_mov_b32 s1, s7
	v_lshl_add_u64 v[56:57], v[148:149], 0, s[0:1]
	s_mov_b64 s[0:1], 0xe800
	v_addc_co_u32_e32 v53, vcc, 0, v117, vcc
	v_lshl_add_u64 v[64:65], v[116:117], 0, s[0:1]
	s_mov_b32 s0, 0xe000
	v_add_co_u32_e32 v60, vcc, s0, v116
	s_or_b32 s0, s6, 0x140
	s_mov_b32 s1, s7
	v_lshl_add_u64 v[68:69], v[148:149], 0, s[0:1]
	s_mov_b64 s[0:1], 0x11000
	v_addc_co_u32_e32 v61, vcc, 0, v117, vcc
	v_lshl_add_u64 v[76:77], v[116:117], 0, s[0:1]
	s_mov_b32 s0, 0x11000
	v_add_co_u32_e32 v72, vcc, s0, v116
	s_or_b32 s0, s6, 0x180
	s_mov_b32 s1, s7
	v_addc_co_u32_e32 v73, vcc, 0, v117, vcc
	v_lshl_add_u64 v[80:81], v[148:149], 0, s[0:1]
	s_mov_b64 s[0:1], 0x13800
	v_lshl_add_u64 v[8:9], v[148:149], 0, s[6:7]
	v_lshl_add_u64 v[120:121], v[116:117], 0, s[0:1]
	v_add_co_u32_e32 v116, vcc, 0x13000, v116
	s_or_b32 s6, s6, 0x1c0
	s_nop 0
	v_addc_co_u32_e32 v117, vcc, 0, v117, vcc
	v_lshl_add_u64 v[148:149], v[148:149], 0, s[6:7]
	global_load_dwordx4 v[0:3], v[0:1], off
	s_nop 0
	global_load_dwordx4 v[4:7], v[4:5], off offset:64
	s_nop 0
	global_load_dwordx4 v[12:15], v[8:9], off
	s_nop 0
	global_load_dwordx4 v[8:11], v[10:11], off offset:64
	s_nop 0
	global_load_dwordx4 v[16:19], v[16:17], off offset:2048
	s_nop 0
	global_load_dwordx4 v[20:23], v[20:21], off
	s_nop 0
	global_load_dwordx4 v[24:27], v[24:25], off
	s_nop 0
	global_load_dwordx4 v[28:31], v[28:29], off offset:64
	s_nop 0
	global_load_dwordx4 v[36:39], v[32:33], off
	s_nop 0
	global_load_dwordx4 v[32:35], v[34:35], off offset:64
	s_nop 0
	global_load_dwordx4 v[40:43], v[40:41], off offset:2048
	s_nop 0
	global_load_dwordx4 v[44:47], v[44:45], off
	s_nop 0
	global_load_dwordx4 v[48:51], v[48:49], off offset:64
	s_nop 0
	global_load_dwordx4 v[52:55], v[52:53], off
	s_nop 0
	global_load_dwordx4 v[56:59], v[56:57], off
	s_nop 0
	global_load_dwordx4 v[60:63], v[60:61], off offset:2048
	s_nop 0
	global_load_dwordx4 v[64:67], v[64:65], off offset:64
	s_nop 0
	global_load_dwordx4 v[68:71], v[68:69], off
	s_nop 0
	global_load_dwordx4 v[72:75], v[72:73], off
	s_nop 0
	global_load_dwordx4 v[76:79], v[76:77], off offset:64
	s_nop 0
	global_load_dwordx4 v[80:83], v[80:81], off
	s_nop 0
	global_load_dwordx4 v[116:119], v[116:117], off offset:2048
	s_nop 0
	global_load_dwordx4 v[120:123], v[120:121], off offset:64
	s_nop 0
	global_load_dwordx4 v[148:151], v[148:149], off
	v_cmp_eq_u32_e32 vcc, 0, v176
	s_and_saveexec_b64 s[98:99], vcc
	s_cbranch_execz .Lreq_q1b
	v_mov_b32_e32 v252, 0
	v_mov_b32_e32 v253, 1
	global_atomic_add v253, v252, v253, s[18:19] sc0

; __global__ void __launch_bounds__(512) hybrid_fwd(Params p) {
;   extern __shared__ __attribute__((aligned(16))) char smem[];
;   __builtin_assume(__builtin_amdgcn_workitem_id_y() == 0);
;   __builtin_assume(__builtin_amdgcn_workitem_id_z() == 0);
;   cg::grid_group grid = cg::this_grid();
;   const int wv = __builtin_amdgcn_readfirstlane((int)(threadIdx.x >> 6));
;     ...
;   run_layer<0>(p, smem, grid, xb, wv);
;   xcd_barrier(xb, wv);
;   run_layer<1>(p, smem, grid, xb, wv);
; }
	.amdhsa_kernel _Z10hybrid_fwd6Params
		.amdhsa_group_segment_fixed_size 0
		.amdhsa_private_segment_fixed_size 0
		.amdhsa_kernarg_size 400
		.amdhsa_user_sgpr_count 2
		.amdhsa_user_sgpr_dispatch_ptr 0
		.amdhsa_user_sgpr_queue_ptr 0
		.amdhsa_user_sgpr_kernarg_segment_ptr 1
		.amdhsa_user_sgpr_dispatch_id 0
		.amdhsa_user_sgpr_kernarg_preload_length 0
		.amdhsa_user_sgpr_kernarg_preload_offset 0
		.amdhsa_user_sgpr_private_segment_size 0
		.amdhsa_uses_dynamic_stack 0
		.amdhsa_enable_private_segment 0
		.amdhsa_system_sgpr_workgroup_id_x 1
		.amdhsa_system_sgpr_workgroup_id_y 0
		.amdhsa_system_sgpr_workgroup_id_z 0
		.amdhsa_system_sgpr_workgroup_info 0
		.amdhsa_system_vgpr_workitem_id 0
		.amdhsa_next_free_vgpr 256
		.amdhsa_next_free_sgpr 100
		.amdhsa_accum_offset 256
		.amdhsa_reserve_vcc 1
		.amdhsa_float_round_mode_32 0
		.amdhsa_float_round_mode_16_64 0
		.amdhsa_float_denorm_mode_32 3
		.amdhsa_float_denorm_mode_16_64 3
		.amdhsa_dx10_clamp 1
		.amdhsa_ieee_mode 1
		.amdhsa_fp16_overflow 0
		.amdhsa_tg_split 0
		.amdhsa_exception_fp_ieee_invalid_op 0
		.amdhsa_exception_fp_denorm_src 0
		.amdhsa_exception_fp_ieee_div_zero 0
		.amdhsa_exception_fp_ieee_overflow 0
		.amdhsa_exception_fp_ieee_underflow 0
		.amdhsa_exception_fp_ieee_inexact 0
		.amdhsa_exception_int_div_zero 0
	.end_amdhsa_kernel

; __global__ void __launch_bounds__(512) hybrid_fwd(Params p) {
;   extern __shared__ __attribute__((aligned(16))) char smem[];
;   __builtin_assume(__builtin_amdgcn_workitem_id_y() == 0);
;   __builtin_assume(__builtin_amdgcn_workitem_id_z() == 0);
;   cg::grid_group grid = cg::this_grid();
;   const int wv = __builtin_amdgcn_readfirstlane((int)(threadIdx.x >> 6));
;     ...
;   run_layer<0>(p, smem, grid, xb, wv);
;   xcd_barrier(xb, wv);
;   run_layer<1>(p, smem, grid, xb, wv);
; }
amdhsa.kernels:
  - .agpr_count:     0
    .args:
      - .offset:         0
        .size:           144
        .value_kind:     by_value
      - .offset:         144
        .size:           4
        .value_kind:     hidden_block_count_x
      - .offset:         148
        .size:           4
        .value_kind:     hidden_block_count_y
      - .offset:         152
        .size:           4
        .value_kind:     hidden_block_count_z
      - .offset:         156
        .size:           2
        .value_kind:     hidden_group_size_x
      - .offset:         158
        .size:           2
        .value_kind:     hidden_group_size_y
      - .offset:         160
        .size:           2
        .value_kind:     hidden_group_size_z
      - .offset:         162
        .size:           2
        .value_kind:     hidden_remainder_x
      - .offset:         164
        .size:           2
        .value_kind:     hidden_remainder_y
      - .offset:         166
        .size:           2
        .value_kind:     hidden_remainder_z
      - .offset:         184
        .size:           8
        .value_kind:     hidden_global_offset_x
      - .offset:         192
        .size:           8
        .value_kind:     hidden_global_offset_y
      - .offset:         200
        .size:           8
        .value_kind:     hidden_global_offset_z
      - .offset:         208
        .size:           2
        .value_kind:     hidden_grid_dims
      - .offset:         232
        .size:           8
        .value_kind:     hidden_multigrid_sync_arg
      - .offset:         264
        .size:           4
        .value_kind:     hidden_dynamic_lds_size
    .group_segment_fixed_size: 0
    .kernarg_segment_align: 8
    .kernarg_segment_size: 400
    .language:       OpenCL C
    .language_version:
      - 2
      - 0
    .max_flat_workgroup_size: 512
    .name:           _Z10hybrid_fwd6Params
    .private_segment_fixed_size: 0
    .sgpr_count:     106
    .sgpr_spill_count: 107
    .symbol:         _Z10hybrid_fwd6Params.kd
    .uniform_work_group_size: 1
    .uses_dynamic_stack: false
    .vgpr_count:     256
    .vgpr_spill_count: 0
    .wavefront_size: 64
